# E48: E46b plus conv split-K exchange-add reads issued one group ahead (double-buffered fragment registers, counted lgkmcnt)
# speedup vs baseline: 1.0020x; 1.0020x over previous
.LBB0_2176:
	s_and_b64 vcc, exec, s[4:5]
	s_waitcnt lgkmcnt(0)
	s_barrier
	s_cbranch_vccnz .LBB0_2178
	ds_read_b128 v[204:207], v203
	ds_read_b128 v[208:211], v203 offset:1024
	ds_read_b128 v[212:215], v203 offset:2048
	ds_read_b128 v[216:219], v203 offset:3072
	ds_read_b128 v[224:227], v203 offset:4096
	ds_read_b128 v[228:231], v203 offset:5120
	ds_read_b128 v[232:235], v203 offset:6144
	ds_read_b128 v[244:247], v203 offset:7168
	s_waitcnt lgkmcnt(7)
	v_pk_add_f32 v[2:3], v[2:3], v[206:207]
	s_waitcnt lgkmcnt(6)
	v_pk_add_f32 v[6:7], v[6:7], v[210:211]
	s_waitcnt lgkmcnt(5)
	v_pk_add_f32 v[10:11], v[10:11], v[214:215]
	s_waitcnt lgkmcnt(4)
	v_pk_add_f32 v[14:15], v[14:15], v[218:219]
	v_pk_add_f32 v[12:13], v[12:13], v[216:217]
	v_pk_add_f32 v[8:9], v[8:9], v[212:213]
	v_pk_add_f32 v[4:5], v[4:5], v[208:209]
	v_pk_add_f32 v[0:1], v[0:1], v[204:205]
	ds_read_b128 v[204:207], v203 offset:8192
	ds_read_b128 v[208:211], v203 offset:9216
	ds_read_b128 v[212:215], v203 offset:10240
	ds_read_b128 v[216:219], v203 offset:11264
	s_waitcnt lgkmcnt(7)
	v_pk_add_f32 v[18:19], v[18:19], v[226:227]
	s_waitcnt lgkmcnt(6)
	v_pk_add_f32 v[22:23], v[22:23], v[230:231]
	s_waitcnt lgkmcnt(5)
	v_pk_add_f32 v[26:27], v[26:27], v[234:235]
	s_waitcnt lgkmcnt(4)
	v_pk_add_f32 v[30:31], v[30:31], v[246:247]
	v_pk_add_f32 v[28:29], v[28:29], v[244:245]
	v_pk_add_f32 v[24:25], v[24:25], v[232:233]
	v_pk_add_f32 v[20:21], v[20:21], v[228:229]
	v_pk_add_f32 v[16:17], v[16:17], v[224:225]
	ds_read_b128 v[224:227], v203 offset:12288
	ds_read_b128 v[228:231], v203 offset:13312
	ds_read_b128 v[232:235], v203 offset:14336
	ds_read_b128 v[244:247], v203 offset:15360
	s_waitcnt lgkmcnt(7)
	v_pk_add_f32 v[34:35], v[34:35], v[206:207]
	s_waitcnt lgkmcnt(6)
	v_pk_add_f32 v[38:39], v[38:39], v[210:211]
	s_waitcnt lgkmcnt(5)
	v_pk_add_f32 v[42:43], v[42:43], v[214:215]
	s_waitcnt lgkmcnt(4)
	v_pk_add_f32 v[46:47], v[46:47], v[218:219]
	v_pk_add_f32 v[44:45], v[44:45], v[216:217]
	v_pk_add_f32 v[40:41], v[40:41], v[212:213]
	v_pk_add_f32 v[36:37], v[36:37], v[208:209]
	v_pk_add_f32 v[32:33], v[32:33], v[204:205]
	ds_read_b128 v[204:207], v203 offset:16384
	ds_read_b128 v[208:211], v203 offset:17408
	ds_read_b128 v[212:215], v203 offset:18432
	ds_read_b128 v[216:219], v203 offset:19456
	s_waitcnt lgkmcnt(7)
	v_pk_add_f32 v[50:51], v[50:51], v[226:227]
	s_waitcnt lgkmcnt(6)
	v_pk_add_f32 v[54:55], v[54:55], v[230:231]
	s_waitcnt lgkmcnt(5)
	v_pk_add_f32 v[58:59], v[58:59], v[234:235]
	s_waitcnt lgkmcnt(4)
	v_pk_add_f32 v[62:63], v[62:63], v[246:247]
	v_pk_add_f32 v[60:61], v[60:61], v[244:245]
	v_pk_add_f32 v[56:57], v[56:57], v[232:233]
	v_pk_add_f32 v[52:53], v[52:53], v[228:229]
	v_pk_add_f32 v[48:49], v[48:49], v[224:225]
	ds_read_b128 v[224:227], v203 offset:20480
	ds_read_b128 v[228:231], v203 offset:21504
	ds_read_b128 v[232:235], v203 offset:22528
	ds_read_b128 v[244:247], v203 offset:23552
	s_waitcnt lgkmcnt(7)
	v_pk_add_f32 v[66:67], v[66:67], v[206:207]
	s_waitcnt lgkmcnt(6)
	v_pk_add_f32 v[70:71], v[70:71], v[210:211]
	s_waitcnt lgkmcnt(5)
	v_pk_add_f32 v[74:75], v[74:75], v[214:215]
	s_waitcnt lgkmcnt(4)
	v_pk_add_f32 v[78:79], v[78:79], v[218:219]
	v_pk_add_f32 v[76:77], v[76:77], v[216:217]
	v_pk_add_f32 v[72:73], v[72:73], v[212:213]
	v_pk_add_f32 v[68:69], v[68:69], v[208:209]
	v_pk_add_f32 v[64:65], v[64:65], v[204:205]
	ds_read_b128 v[204:207], v203 offset:24576
	ds_read_b128 v[208:211], v203 offset:25600
	ds_read_b128 v[212:215], v203 offset:26624
	ds_read_b128 v[216:219], v203 offset:27648
	s_waitcnt lgkmcnt(7)
	v_pk_add_f32 v[82:83], v[82:83], v[226:227]
	s_waitcnt lgkmcnt(6)
	v_pk_add_f32 v[86:87], v[86:87], v[230:231]
	s_waitcnt lgkmcnt(5)
	v_pk_add_f32 v[90:91], v[90:91], v[234:235]
	s_waitcnt lgkmcnt(4)
	v_pk_add_f32 v[94:95], v[94:95], v[246:247]
	v_pk_add_f32 v[92:93], v[92:93], v[244:245]
	v_pk_add_f32 v[88:89], v[88:89], v[232:233]
	v_pk_add_f32 v[84:85], v[84:85], v[228:229]
	v_pk_add_f32 v[80:81], v[80:81], v[224:225]
	ds_read_b128 v[224:227], v203 offset:28672
	ds_read_b128 v[228:231], v203 offset:29696
	ds_read_b128 v[232:235], v203 offset:30720
	ds_read_b128 v[244:247], v203 offset:31744
	s_waitcnt lgkmcnt(7)
	v_pk_add_f32 v[98:99], v[98:99], v[206:207]
	s_waitcnt lgkmcnt(6)
	v_pk_add_f32 v[102:103], v[102:103], v[210:211]
	s_waitcnt lgkmcnt(5)
	v_pk_add_f32 v[106:107], v[106:107], v[214:215]
	s_waitcnt lgkmcnt(4)
	v_pk_add_f32 v[110:111], v[110:111], v[218:219]
	v_pk_add_f32 v[108:109], v[108:109], v[216:217]
	v_pk_add_f32 v[104:105], v[104:105], v[212:213]
	v_pk_add_f32 v[100:101], v[100:101], v[208:209]
	v_pk_add_f32 v[96:97], v[96:97], v[204:205]
	s_waitcnt lgkmcnt(3)
	v_pk_add_f32 v[114:115], v[114:115], v[226:227]
	s_waitcnt lgkmcnt(2)
	v_pk_add_f32 v[118:119], v[118:119], v[230:231]
	s_waitcnt lgkmcnt(1)
	v_pk_add_f32 v[122:123], v[122:123], v[234:235]
	s_waitcnt lgkmcnt(0)
	v_pk_add_f32 v[126:127], v[126:127], v[246:247]
	v_pk_add_f32 v[124:125], v[124:125], v[244:245]
	v_pk_add_f32 v[120:121], v[120:121], v[232:233]
	v_pk_add_f32 v[116:117], v[116:117], v[228:229]
	v_pk_add_f32 v[112:113], v[112:113], v[224:225]
